# plus KV-projection epilogue: all eight row groups' statistics / rotary-key lines touched up front (prefetch loads)
# speedup vs baseline: 1.0211x; 1.0035x over previous
; DI unsigned pk2(float lo, float hi) { const f32x2 v = {lo, hi}; const hwbf16x2 b = __builtin_convertvector(v, hwbf16x2); return __builtin_bit_cast(unsigned, b); }
;     DI void operator()(const f32x4 (&acc)[2][2][4][2], const pg8::Unit& u, int wr, int wc, int fr, int fq) const {
;         asm volatile("" : "+v"(fr), "+v"(fq));
;         const int row0 = u.pm * 256 + wr * 64 + fr, col0 = wc * 32 + 8 * fq;
;         bf16_t* dst = u.pn == 0 ? Kb : Vb;
; #pragma unroll
;         for (int ai = 0; ai < 2; ++ai)
; #pragma unroll
;             for (int m = 0; m < 4; ++m) {
;                 const int row = row0 + ai * 128 + m * 16; const f32x4 p = *(const f32x4*)(SSQ + (size_t)row * 4);
;                 const float rs = __builtin_amdgcn_rsqf(((p[0] + p[1]) + (p[2] + p[3])) * (1.0f / 128.0f) + EPS);
; #pragma unroll
;                 for (int bj = 0; bj < 2; ++bj) { f32x4 v0 = acc[ai][bj][m][0] * rs, v1 = acc[ai][bj][m][1] * rs;
;                     if (u.pn == 0 && (wc & 1)) {
;                         if (fq < 2) { const u32x2 a = *(const u32x2*)(H + (size_t)row * HP + C_KR + 4 * fq), b = *(const u32x2*)(H + (size_t)row * HP + C_KR + 8 + 4 * fq);
;                             v0 = (f32x4){__uint_as_float(a.x << 16), __uint_as_float(a.x & 0xffff0000u), __uint_as_float(a.y << 16), __uint_as_float(a.y & 0xffff0000u)};
;                             v1 = (f32x4){__uint_as_float(b.x << 16), __uint_as_float(b.x & 0xffff0000u), __uint_as_float(b.y << 16), __uint_as_float(b.y & 0xffff0000u)};
;                             rope4(v0, v1, ROPE16 + (size_t)row * 16, fq); }
;                         else { v0 = (f32x4){0.f, 0.f, 0.f, 0.f}; v1 = v0; }
;                     }
;                     u32x4 w; w.x = pk2(v0[0], v0[1]); w.y = pk2(v0[2], v0[3]); w.z = pk2(v1[0], v1[1]); w.w = pk2(v1[2], v1[3]);
;                     *(u32x4*)(dst + (size_t)row * 256 + bj * 128 + col0) = w; }
.LBB0_891:
	s_lshl_b32 s2, s15, 8
	v_readlane_b32 s3, v255, 5
	v_mov_b32_e32 v136, v152
	v_mov_b32_e32 v137, v153
	s_add_i32 s2, s2, s3
	s_cmp_lg_u32 s48, 0
	v_add_u32_e32 v140, s2, v136
	v_ashrrev_i32_e32 v141, 31, v140
	v_lshl_add_u64 v[142:143], v[140:141], 4, s[28:29]
	global_load_dwordx4 v[220:223], v[142:143], off offset:256
	global_load_dwordx4 v[224:227], v[142:143], off offset:512
	global_load_dwordx4 v[228:231], v[142:143], off offset:768
	global_load_dwordx4 v[232:235], v[142:143], off offset:2048
	global_load_dwordx4 v[236:239], v[142:143], off offset:2304
	global_load_dwordx4 v[240:243], v[142:143], off offset:2560
	global_load_dwordx4 v[244:247], v[142:143], off offset:2816
	global_load_dwordx4 v[142:145], v[142:143], off
	v_readlane_b32 s18, v255, 10
	s_cselect_b64 s[2:3], -1, 0
	v_readlane_b32 s19, v255, 11
	v_lshlrev_b32_e32 v136, 3, v137
	s_or_b64 vcc, s[18:19], s[2:3]
	v_lshlrev_b32_e32 v138, 2, v137
	v_mad_i64_i32 v[148:149], s[34:35], v140, s73, 0
	v_lshlrev_b64 v[150:151], 6, v[140:141]
	s_xor_b64 s[2:3], vcc, -1
	v_cmp_gt_i32_e64 s[18:19], 2, v137
	v_ashrrev_i32_e32 v139, 31, v138
	v_ashrrev_i32_e32 v137, 31, v136
	s_and_b64 s[18:19], s[2:3], s[18:19]
	s_waitcnt vmcnt(0)
	v_mov_b32_e32 v146, v143
	v_mov_b32_e32 v147, v144
	v_mov_b32_e32 v143, v145
	v_pk_add_f32 v[142:143], v[146:147], v[142:143]
	s_nop 0
	v_add_f32_e32 v142, v142, v143
	v_fmamk_f32 v142, v142, 0x3c000000, v202
	v_rsq_f32_e32 v142, v142
	s_nop 0
	v_pk_mul_f32 v[122:123], v[122:123], v[142:143] op_sel_hi:[1,0]
	v_pk_mul_f32 v[146:147], v[128:129], v[142:143] op_sel_hi:[1,0]
	v_pk_mul_f32 v[126:127], v[126:127], v[142:143] op_sel_hi:[1,0]
	v_pk_mul_f32 v[124:125], v[124:125], v[142:143] op_sel_hi:[1,0]
	v_cndmask_b32_e32 v128, 0, v122, vcc
	v_cndmask_b32_e32 v129, 0, v123, vcc
	v_lshl_add_u64 v[122:123], s[26:27], 0, v[148:149]
	v_lshl_add_u64 v[148:149], s[22:23], 0, v[150:151]
	v_cndmask_b32_e32 v144, 0, v124, vcc
	v_cndmask_b32_e32 v145, 0, v125, vcc
	v_cndmask_b32_e32 v126, 0, v126, vcc
	v_cndmask_b32_e32 v127, 0, v127, vcc
	v_cndmask_b32_e32 v146, 0, v146, vcc
	v_cndmask_b32_e32 v147, 0, v147, vcc
	v_lshl_add_u64 v[124:125], v[138:139], 1, v[122:123]
	v_lshl_add_u64 v[148:149], v[136:137], 2, v[148:149]
	s_and_saveexec_b64 s[2:3], s[18:19]
	s_cbranch_execz .LBB0_893
	s_mov_b64 s[36:37], 0x18000
	v_lshl_add_u64 v[168:169], v[124:125], 0, s[36:37]
	global_load_dwordx2 v[170:171], v[168:169], off offset:768
	s_mov_b64 s[36:37], 0x400
	v_lshl_add_u64 v[168:169], v[148:149], 0, s[36:37]
	global_load_dwordx4 v[172:175], v[168:169], off
	s_mov_b64 s[36:37], 0x30000
	v_lshl_add_u64 v[168:169], v[124:125], 0, s[36:37]
	global_load_dwordx2 v[170:171], v[168:169], off offset:768
	s_mov_b64 s[36:37], 0x800
	v_lshl_add_u64 v[168:169], v[148:149], 0, s[36:37]
	global_load_dwordx4 v[172:175], v[168:169], off
	s_mov_b64 s[36:37], 0x48000
	v_lshl_add_u64 v[168:169], v[124:125], 0, s[36:37]
	global_load_dwordx2 v[170:171], v[168:169], off offset:768
	s_mov_b64 s[36:37], 0xc00
	v_lshl_add_u64 v[168:169], v[148:149], 0, s[36:37]
	global_load_dwordx4 v[172:175], v[168:169], off
	s_mov_b64 s[36:37], 0xc0000
	v_lshl_add_u64 v[168:169], v[124:125], 0, s[36:37]
	global_load_dwordx2 v[170:171], v[168:169], off offset:768
	s_mov_b64 s[36:37], 0x2000
	v_lshl_add_u64 v[168:169], v[148:149], 0, s[36:37]
	global_load_dwordx4 v[172:175], v[168:169], off
	s_mov_b64 s[36:37], 0xd8000
	v_lshl_add_u64 v[168:169], v[124:125], 0, s[36:37]
	global_load_dwordx2 v[170:171], v[168:169], off offset:768
	s_mov_b64 s[36:37], 0x2400
	v_lshl_add_u64 v[168:169], v[148:149], 0, s[36:37]
	global_load_dwordx4 v[172:175], v[168:169], off
	s_mov_b64 s[36:37], 0xf0000
	v_lshl_add_u64 v[168:169], v[124:125], 0, s[36:37]
	global_load_dwordx2 v[170:171], v[168:169], off offset:768
	s_mov_b64 s[36:37], 0x2800
	v_lshl_add_u64 v[168:169], v[148:149], 0, s[36:37]
	global_load_dwordx4 v[172:175], v[168:169], off
	s_mov_b64 s[36:37], 0x108000
	v_lshl_add_u64 v[168:169], v[124:125], 0, s[36:37]
	global_load_dwordx2 v[170:171], v[168:169], off offset:768
	s_mov_b64 s[36:37], 0x2c00
	v_lshl_add_u64 v[168:169], v[148:149], 0, s[36:37]
	global_load_dwordx4 v[172:175], v[168:169], off
	global_load_dwordx2 v[122:123], v[124:125], off offset:768
	global_load_dwordx2 v[150:151], v[124:125], off offset:784
	global_load_dwordx4 v[126:129], v[148:149], off
	global_load_dwordx4 v[144:147], v[148:149], off offset:16
	s_waitcnt vmcnt(3)
	v_lshlrev_b32_e32 v143, 16, v123
	v_lshlrev_b32_e32 v156, 16, v122
	v_and_b32_e32 v157, 0xffff0000, v122
	v_and_b32_e32 v123, 0xffff0000, v123
	s_waitcnt vmcnt(2)
	v_and_b32_e32 v122, 0xffff0000, v151
	v_lshlrev_b32_e32 v163, 16, v151
	v_lshlrev_b32_e32 v158, 16, v150
	v_and_b32_e32 v159, 0xffff0000, v150
	s_waitcnt vmcnt(1)
	v_mov_b32_e32 v160, v127
	v_mov_b32_e32 v161, v129
	v_mov_b32_e32 v127, v128
	s_waitcnt vmcnt(0)
	v_pk_mul_f32 v[166:167], v[146:147], v[122:123] op_sel:[0,1] op_sel_hi:[1,0]
	v_pk_mul_f32 v[122:123], v[146:147], v[122:123]
	v_pk_mul_f32 v[128:129], v[126:127], v[158:159]
	v_pk_mul_f32 v[150:151], v[160:161], v[158:159]
	v_mul_f32_e32 v158, v144, v143
	v_mul_f32_e32 v162, v145, v163
	v_mul_f32_e32 v164, v145, v143
	v_mul_f32_e32 v144, v144, v163
	v_mov_b32_e32 v159, v166
	v_mov_b32_e32 v163, v167
	v_mov_b32_e32 v165, v123
	v_mov_b32_e32 v145, v122
	v_pk_fma_f32 v[126:127], v[126:127], v[156:157], v[150:151] neg_lo:[0,0,1] neg_hi:[0,0,1]
	v_pk_fma_f32 v[128:129], v[160:161], v[156:157], v[128:129]
	v_pk_add_f32 v[146:147], v[158:159], v[162:163] neg_lo:[0,1] neg_hi:[0,1]
	v_pk_add_f32 v[144:145], v[164:165], v[144:145]
